# P7 softmax: exponent build and row sums with packed f32 (v_pk_fma_f32 / v_pk_add_f32), -38 VALU per tile
# speedup vs baseline: 1.0035x; 1.0035x over previous
.LBB0_737:
	s_nop 8
	v_max_f32_e32 v1, v163, v163
	v_max_f32_e32 v12, v162, v162
	v_max_f32_e32 v1, v12, v1
	v_max3_f32 v1, v1, v164, v165
	v_max3_f32 v1, v1, v166, v167
	v_max3_f32 v1, v1, v168, v169
	v_max3_f32 v1, v1, v170, v171
	v_max3_f32 v1, v1, v172, v173
	v_max3_f32 v1, v1, v174, v175
	v_max3_f32 v1, v1, v176, v177
	v_max3_f32 v1, v1, v146, v147
	v_max3_f32 v1, v1, v148, v149
	v_max3_f32 v1, v1, v150, v151
	v_max3_f32 v1, v1, v152, v153
	v_max3_f32 v1, v1, v154, v155
	v_max3_f32 v1, v1, v156, v157
	v_max3_f32 v1, v1, v158, v159
	v_max3_f32 v1, v1, v160, v161
	v_mov_b32_e32 v12, v1
	s_nop 1
	v_permlane32_swap_b32_e32 v1, v12
	v_max_f32_e32 v12, v12, v12
	v_max_f32_e32 v1, v1, v1
	v_max_f32_e32 v1, v1, v12
	v_mul_f32_e32 v12, 0x3e0293ee, v1
	v_fma_f32 v1, v1, s97, -v235
	v_cmp_ge_f32_e32 vcc, s80, v1
	v_max_f32_e32 v1, v235, v235
	v_max_f32_e32 v1, v1, v12
	v_sub_f32_e32 v12, v235, v1
	v_cvt_f32_i32_e32 v13, v234
	s_cmp_eq_u64 vcc, exec
	v_exp_f32_e32 v12, v12
	s_cselect_b64 vcc, -1, 0
	v_cndmask_b32_e32 v235, v1, v235, vcc
	v_fma_f32 v1, -v232, v13, -v235
	v_cndmask_b32_e64 v16, v12, 1.0, vcc
	v_mul_f32_e32 v12, 0x42000000, v232
	v_mov_b32_e32 v252, s97
	v_mov_b32_e32 v253, s97
	v_mov_b32_e32 v13, v12
	v_fmamk_f32 v14, v232, 0x00000000, v1
	v_add_f32_e32 v15, v232, v14
	v_pk_add_f32 v[238:239], v[14:15], v[12:13]
	v_pk_fma_f32 v[162:163], v[162:163], v[252:253], v[14:15]
	v_pk_fma_f32 v[146:147], v[146:147], v[252:253], v[238:239]
	v_exp_f32_e32 v162, v162
	v_exp_f32_e32 v163, v163
	v_exp_f32_e32 v146, v146
	v_exp_f32_e32 v147, v147
	v_fmamk_f32 v14, v232, 0x40000000, v1
	v_add_f32_e32 v15, v232, v14
	v_pk_add_f32 v[238:239], v[14:15], v[12:13]
	v_pk_fma_f32 v[164:165], v[164:165], v[252:253], v[14:15]
	v_pk_fma_f32 v[148:149], v[148:149], v[252:253], v[238:239]
	v_exp_f32_e32 v164, v164
	v_exp_f32_e32 v165, v165
	v_exp_f32_e32 v148, v148
	v_exp_f32_e32 v149, v149
	v_pk_add_f32 v[250:251], v[162:163], v[146:147]
	v_fmamk_f32 v14, v232, 0x41000000, v1
	v_add_f32_e32 v15, v232, v14
	v_pk_add_f32 v[238:239], v[14:15], v[12:13]
	v_pk_fma_f32 v[166:167], v[166:167], v[252:253], v[14:15]
	v_pk_fma_f32 v[150:151], v[150:151], v[252:253], v[238:239]
	v_exp_f32_e32 v166, v166
	v_exp_f32_e32 v167, v167
	v_exp_f32_e32 v150, v150
	v_exp_f32_e32 v151, v151
	v_pk_add_f32 v[250:251], v[164:165], v[250:251]
	v_pk_add_f32 v[250:251], v[148:149], v[250:251]
	v_fmamk_f32 v14, v232, 0x41200000, v1
	v_add_f32_e32 v15, v232, v14
	v_pk_add_f32 v[238:239], v[14:15], v[12:13]
	v_pk_fma_f32 v[168:169], v[168:169], v[252:253], v[14:15]
	v_pk_fma_f32 v[152:153], v[152:153], v[252:253], v[238:239]
	v_exp_f32_e32 v168, v168
	v_exp_f32_e32 v169, v169
	v_exp_f32_e32 v152, v152
	v_exp_f32_e32 v153, v153
	v_pk_add_f32 v[250:251], v[166:167], v[250:251]
	v_pk_add_f32 v[250:251], v[150:151], v[250:251]
	v_fmamk_f32 v14, v232, 0x41800000, v1
	v_add_f32_e32 v15, v232, v14
	v_pk_add_f32 v[238:239], v[14:15], v[12:13]
	v_pk_fma_f32 v[170:171], v[170:171], v[252:253], v[14:15]
	v_pk_fma_f32 v[154:155], v[154:155], v[252:253], v[238:239]
	v_exp_f32_e32 v170, v170
	v_exp_f32_e32 v171, v171
	v_exp_f32_e32 v154, v154
	v_exp_f32_e32 v155, v155
	v_pk_add_f32 v[250:251], v[168:169], v[250:251]
	v_pk_add_f32 v[250:251], v[152:153], v[250:251]
	v_fmamk_f32 v14, v232, 0x41900000, v1
	v_add_f32_e32 v15, v232, v14
	v_pk_add_f32 v[238:239], v[14:15], v[12:13]
	v_pk_fma_f32 v[172:173], v[172:173], v[252:253], v[14:15]
	v_pk_fma_f32 v[156:157], v[156:157], v[252:253], v[238:239]
	v_exp_f32_e32 v172, v172
	v_exp_f32_e32 v173, v173
	v_exp_f32_e32 v156, v156
	v_exp_f32_e32 v157, v157
	v_pk_add_f32 v[250:251], v[170:171], v[250:251]
	v_pk_add_f32 v[250:251], v[154:155], v[250:251]
	v_fmamk_f32 v14, v232, 0x41c00000, v1
	v_add_f32_e32 v15, v232, v14
	v_pk_add_f32 v[238:239], v[14:15], v[12:13]
	v_pk_fma_f32 v[174:175], v[174:175], v[252:253], v[14:15]
	v_pk_fma_f32 v[158:159], v[158:159], v[252:253], v[238:239]
	v_exp_f32_e32 v174, v174
	v_exp_f32_e32 v175, v175
	v_exp_f32_e32 v158, v158
	v_exp_f32_e32 v159, v159
	v_pk_add_f32 v[250:251], v[172:173], v[250:251]
	v_pk_add_f32 v[250:251], v[156:157], v[250:251]
	v_fmamk_f32 v14, v232, 0x41d00000, v1
	v_add_f32_e32 v15, v232, v14
	v_pk_add_f32 v[238:239], v[14:15], v[12:13]
	v_pk_fma_f32 v[176:177], v[176:177], v[252:253], v[14:15]
	v_pk_fma_f32 v[160:161], v[160:161], v[252:253], v[238:239]
	v_exp_f32_e32 v176, v176
	v_exp_f32_e32 v177, v177
	v_exp_f32_e32 v160, v160
	v_exp_f32_e32 v161, v161
	v_pk_add_f32 v[250:251], v[174:175], v[250:251]
	v_pk_add_f32 v[250:251], v[158:159], v[250:251]
	s_nop 0
	v_pk_add_f32 v[250:251], v[176:177], v[250:251]
	v_pk_add_f32 v[250:251], v[160:161], v[250:251]
	v_cvt_pk_bf16_f32 v12, v146, v147
	v_cvt_pk_bf16_f32 v13, v148, v149
	v_cvt_pk_bf16_f32 v14, v150, v151
	v_cvt_pk_bf16_f32 v15, v152, v153
	v_cvt_pk_bf16_f32 v146, v154, v155
	v_cvt_pk_bf16_f32 v147, v156, v157
	v_cvt_pk_bf16_f32 v148, v158, v159
	v_cvt_pk_bf16_f32 v149, v160, v161
	v_add_f32_e32 v17, v250, v251
	v_cvt_pk_bf16_f32 v150, v162, v163
	v_cvt_pk_bf16_f32 v151, v164, v165
	v_cvt_pk_bf16_f32 v152, v166, v167
	v_cvt_pk_bf16_f32 v153, v168, v169
	v_cvt_pk_bf16_f32 v154, v170, v171
	v_cvt_pk_bf16_f32 v155, v172, v173
	v_cvt_pk_bf16_f32 v156, v174, v175
	v_mov_b32_e32 v174, v17
	v_cvt_pk_bf16_f32 v157, v176, v177
	v_cmp_neq_f32_e32 vcc, 0, v236
	s_nop 0
	v_permlane32_swap_b32_e32 v17, v174
	v_permlane32_swap_b32_e32 v150, v152
	v_permlane32_swap_b32_e32 v151, v153
	v_permlane32_swap_b32_e32 v154, v156
	v_permlane32_swap_b32_e32 v155, v157
	v_permlane32_swap_b32_e32 v12, v14
	v_permlane32_swap_b32_e32 v13, v15
	v_permlane32_swap_b32_e32 v146, v148
	v_permlane32_swap_b32_e32 v147, v149
	s_cbranch_vccz .LBB0_730
	v_cmp_gt_f32_e32 vcc, 1.0, v16
	s_cbranch_vccz .LBB0_730
	s_and_saveexec_b64 s[6:7], s[4:5]
	s_cbranch_execz .LBB0_729
	ds_write_b32 v223, v16
	s_branch .LBB0_729

.LBB0_758:
	s_nop 8
	v_max_f32_e32 v1, v163, v163
	v_max_f32_e32 v12, v162, v162
	v_max_f32_e32 v1, v12, v1
	v_max3_f32 v1, v1, v164, v165
	v_max3_f32 v1, v1, v166, v167
	v_max3_f32 v1, v1, v168, v169
	v_max3_f32 v1, v1, v170, v171
	v_max3_f32 v1, v1, v172, v173
	v_max3_f32 v1, v1, v174, v175
	v_max3_f32 v1, v1, v176, v177
	v_max3_f32 v1, v1, v146, v147
	v_max3_f32 v1, v1, v148, v149
	v_max3_f32 v1, v1, v150, v151
	v_max3_f32 v1, v1, v152, v153
	v_max3_f32 v1, v1, v154, v155
	v_max3_f32 v1, v1, v156, v157
	v_max3_f32 v1, v1, v158, v159
	v_max3_f32 v1, v1, v160, v161
	v_mov_b32_e32 v12, v1
	s_nop 1
	v_permlane32_swap_b32_e32 v1, v12
	v_max_f32_e32 v12, v12, v12
	v_max_f32_e32 v1, v1, v1
	v_max_f32_e32 v1, v1, v12
	v_mul_f32_e32 v12, 0x3e0293ee, v1
	v_fma_f32 v1, v1, s97, -v235
	v_cmp_ge_f32_e32 vcc, s80, v1
	v_max_f32_e32 v1, v235, v235
	v_max_f32_e32 v1, v1, v12
	v_sub_f32_e32 v12, v235, v1
	v_cvt_f32_i32_e32 v13, v234
	s_cmp_eq_u64 vcc, exec
	v_exp_f32_e32 v12, v12
	s_cselect_b64 vcc, -1, 0
	v_cndmask_b32_e32 v235, v1, v235, vcc
	v_fma_f32 v1, -v228, v13, -v235
	v_cndmask_b32_e64 v16, v12, 1.0, vcc
	v_mul_f32_e32 v12, 0x42000000, v228
	v_mov_b32_e32 v252, s97
	v_mov_b32_e32 v253, s97
	v_mov_b32_e32 v13, v12
	v_fmamk_f32 v14, v228, 0x00000000, v1
	v_add_f32_e32 v15, v228, v14
	v_pk_add_f32 v[238:239], v[14:15], v[12:13]
	v_pk_fma_f32 v[162:163], v[162:163], v[252:253], v[14:15]
	v_pk_fma_f32 v[146:147], v[146:147], v[252:253], v[238:239]
	v_exp_f32_e32 v162, v162
	v_exp_f32_e32 v163, v163
	v_exp_f32_e32 v146, v146
	v_exp_f32_e32 v147, v147
	v_fmamk_f32 v14, v228, 0x40000000, v1
	v_add_f32_e32 v15, v228, v14
	v_pk_add_f32 v[238:239], v[14:15], v[12:13]
	v_pk_fma_f32 v[164:165], v[164:165], v[252:253], v[14:15]
	v_pk_fma_f32 v[148:149], v[148:149], v[252:253], v[238:239]
	v_exp_f32_e32 v164, v164
	v_exp_f32_e32 v165, v165
	v_exp_f32_e32 v148, v148
	v_exp_f32_e32 v149, v149
	v_pk_add_f32 v[250:251], v[162:163], v[146:147]
	v_fmamk_f32 v14, v228, 0x41000000, v1
	v_add_f32_e32 v15, v228, v14
	v_pk_add_f32 v[238:239], v[14:15], v[12:13]
	v_pk_fma_f32 v[166:167], v[166:167], v[252:253], v[14:15]
	v_pk_fma_f32 v[150:151], v[150:151], v[252:253], v[238:239]
	v_exp_f32_e32 v166, v166
	v_exp_f32_e32 v167, v167
	v_exp_f32_e32 v150, v150
	v_exp_f32_e32 v151, v151
	v_pk_add_f32 v[250:251], v[164:165], v[250:251]
	v_pk_add_f32 v[250:251], v[148:149], v[250:251]
	v_fmamk_f32 v14, v228, 0x41200000, v1
	v_add_f32_e32 v15, v228, v14
	v_pk_add_f32 v[238:239], v[14:15], v[12:13]
	v_pk_fma_f32 v[168:169], v[168:169], v[252:253], v[14:15]
	v_pk_fma_f32 v[152:153], v[152:153], v[252:253], v[238:239]
	v_exp_f32_e32 v168, v168
	v_exp_f32_e32 v169, v169
	v_exp_f32_e32 v152, v152
	v_exp_f32_e32 v153, v153
	v_pk_add_f32 v[250:251], v[166:167], v[250:251]
	v_pk_add_f32 v[250:251], v[150:151], v[250:251]
	v_fmamk_f32 v14, v228, 0x41800000, v1
	v_add_f32_e32 v15, v228, v14
	v_pk_add_f32 v[238:239], v[14:15], v[12:13]
	v_pk_fma_f32 v[170:171], v[170:171], v[252:253], v[14:15]
	v_pk_fma_f32 v[154:155], v[154:155], v[252:253], v[238:239]
	v_exp_f32_e32 v170, v170
	v_exp_f32_e32 v171, v171
	v_exp_f32_e32 v154, v154
	v_exp_f32_e32 v155, v155
	v_pk_add_f32 v[250:251], v[168:169], v[250:251]
	v_pk_add_f32 v[250:251], v[152:153], v[250:251]
	v_fmamk_f32 v14, v228, 0x41900000, v1
	v_add_f32_e32 v15, v228, v14
	v_pk_add_f32 v[238:239], v[14:15], v[12:13]
	v_pk_fma_f32 v[172:173], v[172:173], v[252:253], v[14:15]
	v_pk_fma_f32 v[156:157], v[156:157], v[252:253], v[238:239]
	v_exp_f32_e32 v172, v172
	v_exp_f32_e32 v173, v173
	v_exp_f32_e32 v156, v156
	v_exp_f32_e32 v157, v157
	v_pk_add_f32 v[250:251], v[170:171], v[250:251]
	v_pk_add_f32 v[250:251], v[154:155], v[250:251]
	v_fmamk_f32 v14, v228, 0x41c00000, v1
	v_add_f32_e32 v15, v228, v14
	v_pk_add_f32 v[238:239], v[14:15], v[12:13]
	v_pk_fma_f32 v[174:175], v[174:175], v[252:253], v[14:15]
	v_pk_fma_f32 v[158:159], v[158:159], v[252:253], v[238:239]
	v_exp_f32_e32 v174, v174
	v_exp_f32_e32 v175, v175
	v_exp_f32_e32 v158, v158
	v_exp_f32_e32 v159, v159
	v_pk_add_f32 v[250:251], v[172:173], v[250:251]
	v_pk_add_f32 v[250:251], v[156:157], v[250:251]
	v_fmamk_f32 v14, v228, 0x41d00000, v1
	v_add_f32_e32 v15, v228, v14
	v_pk_add_f32 v[238:239], v[14:15], v[12:13]
	v_pk_fma_f32 v[176:177], v[176:177], v[252:253], v[14:15]
	v_pk_fma_f32 v[160:161], v[160:161], v[252:253], v[238:239]
	v_exp_f32_e32 v176, v176
	v_exp_f32_e32 v177, v177
	v_exp_f32_e32 v160, v160
	v_exp_f32_e32 v161, v161
	v_pk_add_f32 v[250:251], v[174:175], v[250:251]
	v_pk_add_f32 v[250:251], v[158:159], v[250:251]
	s_nop 0
	v_pk_add_f32 v[250:251], v[176:177], v[250:251]
	v_pk_add_f32 v[250:251], v[160:161], v[250:251]
	v_cvt_pk_bf16_f32 v12, v146, v147
	v_cvt_pk_bf16_f32 v13, v148, v149
	v_cvt_pk_bf16_f32 v14, v150, v151
	v_cvt_pk_bf16_f32 v15, v152, v153
	v_cvt_pk_bf16_f32 v146, v154, v155
	v_cvt_pk_bf16_f32 v147, v156, v157
	v_cvt_pk_bf16_f32 v148, v158, v159
	v_cvt_pk_bf16_f32 v149, v160, v161
	v_add_f32_e32 v17, v250, v251
	v_cvt_pk_bf16_f32 v150, v162, v163
	v_cvt_pk_bf16_f32 v151, v164, v165
	v_cvt_pk_bf16_f32 v152, v166, v167
	v_cvt_pk_bf16_f32 v153, v168, v169
	v_cvt_pk_bf16_f32 v154, v170, v171
	v_cvt_pk_bf16_f32 v155, v172, v173
	v_cvt_pk_bf16_f32 v156, v174, v175
	v_mov_b32_e32 v174, v17
	v_cvt_pk_bf16_f32 v157, v176, v177
	v_cmp_neq_f32_e32 vcc, 0, v236
	s_nop 0
	v_permlane32_swap_b32_e32 v17, v174
	v_permlane32_swap_b32_e32 v150, v152
	v_permlane32_swap_b32_e32 v151, v153
	v_permlane32_swap_b32_e32 v154, v156
	v_permlane32_swap_b32_e32 v155, v157
	v_permlane32_swap_b32_e32 v12, v14
	v_permlane32_swap_b32_e32 v13, v15
	v_permlane32_swap_b32_e32 v146, v148
	v_permlane32_swap_b32_e32 v147, v149
	s_cbranch_vccz .LBB0_751
	v_cmp_gt_f32_e32 vcc, 1.0, v16
	s_cbranch_vccz .LBB0_751
	s_and_saveexec_b64 s[6:7], s[4:5]
	s_cbranch_execz .LBB0_750
	ds_write_b32 v232, v16
	s_branch .LBB0_750
